# GEMM4 fast-path epilogue: removed 26 address-arithmetic VALU ops left dead after the conv weight/bias loads became LDS reads
# speedup vs baseline: 1.0014x; 1.0014x over previous
.LBB0_1227:
	v_and_b32_e32 v248, 0xff, v184
	v_lshlrev_b32_e32 v248, 2, v248
	v_add_u32_e32 v248, 0x24000, v248
	s_ashr_i32 s0, s17, 12
	s_mulk_i32 s0, 0x5800
	s_ashr_i32 s1, s0, 31
	s_add_u32 s0, s68, s0
	s_addc_u32 s1, s69, s1
	v_ashrrev_i32_e32 v185, 31, v184
	s_add_u32 s0, s0, 0x2c000

	s_addc_u32 s1, s1, 0


	ds_read_b128 v[72:75], v248
	ds_read_b128 v[76:79], v248 offset:1024


	ds_read_b128 v[80:83], v248 offset:2048
	ds_read_b128 v[88:91], v248 offset:3072


	ds_read_b128 v[84:87], v248 offset:512
	ds_read_b128 v[92:95], v248 offset:1536


	ds_read_b128 v[96:99], v248 offset:2560
	ds_read_b128 v[100:103], v248 offset:3584
	v_mov_b32_e32 v108, 0
	s_and_b64 vcc, exec, s[60:61]
	v_mov_b32_e32 v112, 0
	v_mov_b32_e32 v113, 0
	v_mov_b32_e32 v114, 0
	v_mov_b32_e32 v115, 0
	v_mov_b32_e32 v66, 0
	v_mov_b32_e32 v67, 0
	v_mov_b32_e32 v68, 0
	v_mov_b32_e32 v69, 0
	s_cbranch_vccnz .LBB0_1229
	ds_read_b128 v[66:69], v221
	ds_read_b128 v[112:115], v222

.LBB0_1235:
	v_pk_fma_f32 v[54:55], v[196:197], v[82:83], v[90:91]
	v_pk_fma_f32 v[108:109], v[194:195], v[80:81], v[88:89]
	v_pk_fma_f32 v[54:55], v[78:79], v[52:53], v[54:55]
	s_waitcnt lgkmcnt(1)
	v_mov_b32_dpp v60, v48 row_shr:1 row_mask:0xf bank_mask:0xf
	v_mov_b32_dpp v61, v49 row_shr:1 row_mask:0xf bank_mask:0xf
	v_pk_fma_f32 v[108:109], v[76:77], v[50:51], v[108:109]
	v_pk_fma_f32 v[54:55], v[74:75], v[106:107], v[54:55]
	v_pk_fma_f32 v[106:107], v[200:201], v[98:99], v[102:103]
	s_waitcnt lgkmcnt(0)
	v_mov_b32_dpp v64, v40 row_shr:1 row_mask:0xf bank_mask:0xf
	v_mov_b32_dpp v65, v41 row_shr:1 row_mask:0xf bank_mask:0xf
	v_pk_fma_f32 v[104:105], v[72:73], v[104:105], v[108:109]
	v_pk_fma_f32 v[106:107], v[94:95], v[60:61], v[106:107]
	v_mov_b32_dpp v58, v46 row_shr:1 row_mask:0xf bank_mask:0xf
	v_pk_fma_f32 v[64:65], v[86:87], v[64:65], v[106:107]
	v_mul_f32_e32 v106, 0xbfb8aa3b, v104
	v_exp_f32_e32 v106, v106
	v_mov_b32_dpp v59, v47 row_shr:1 row_mask:0xf bank_mask:0xf
	v_pk_fma_f32 v[108:109], v[198:199], v[96:97], v[100:101]
	v_mov_b32_dpp v62, v38 row_shr:1 row_mask:0xf bank_mask:0xf
	v_add_f32_e32 v106, 1.0, v106
	v_rcp_f32_e32 v106, v106
	v_mov_b32_dpp v63, v39 row_shr:1 row_mask:0xf bank_mask:0xf
	v_pk_fma_f32 v[108:109], v[92:93], v[58:59], v[108:109]
	v_pk_fma_f32 v[42:43], v[42:43], v[80:81], v[88:89]
	v_pk_fma_f32 v[62:63], v[84:85], v[62:63], v[108:109]
	v_mul_f32_e32 v104, v104, v106
	v_mul_f32_e32 v62, v104, v62
	v_mul_f32_e32 v104, 0xbfb8aa3b, v105
	v_exp_f32_e32 v104, v104
	v_pk_fma_f32 v[44:45], v[44:45], v[82:83], v[90:91]
	s_and_b64 vcc, exec, s[60:61]
	v_add_f32_e32 v104, 1.0, v104
	v_rcp_f32_e32 v104, v104
	s_nop 0
	v_mul_f32_e32 v104, v105, v104
	v_mul_f32_e32 v63, v104, v63
	v_mul_f32_e32 v104, 0xbfb8aa3b, v54
	v_exp_f32_e32 v104, v104
	v_mov_b32_e32 v105, 0
	v_add_f32_e32 v104, 1.0, v104
	v_rcp_f32_e32 v104, v104
	s_nop 0
	v_mul_f32_e32 v54, v54, v104
	v_mul_f32_e32 v64, v54, v64
	v_mul_f32_e32 v54, 0xbfb8aa3b, v55
	v_exp_f32_e32 v54, v54
	v_mov_b32_e32 v104, 0
	v_add_f32_e32 v54, 1.0, v54
	v_rcp_f32_e32 v54, v54
	s_nop 0
	v_mul_f32_e32 v54, v55, v54
	v_mul_f32_e32 v55, v54, v65
	v_cvt_pk_bf16_f32 v54, v62, v63
	v_pk_fma_f32 v[62:63], v[188:189], v[82:83], v[90:91]
	v_cvt_pk_bf16_f32 v55, v64, v55
	v_pk_fma_f32 v[64:65], v[186:187], v[80:81], v[88:89]
	v_pk_fma_f32 v[62:63], v[196:197], v[78:79], v[62:63]
	v_pk_fma_f32 v[64:65], v[194:195], v[76:77], v[64:65]
	v_pk_fma_f32 v[52:53], v[74:75], v[52:53], v[62:63]
	v_pk_fma_f32 v[62:63], v[192:193], v[98:99], v[102:103]
	v_pk_fma_f32 v[50:51], v[72:73], v[50:51], v[64:65]
	v_pk_fma_f32 v[62:63], v[200:201], v[94:95], v[62:63]
	v_pk_fma_f32 v[64:65], v[190:191], v[96:97], v[100:101]
	v_pk_fma_f32 v[60:61], v[86:87], v[60:61], v[62:63]
	v_mul_f32_e32 v62, 0xbfb8aa3b, v50
	v_exp_f32_e32 v62, v62
	v_pk_fma_f32 v[64:65], v[198:199], v[92:93], v[64:65]
	v_add_f32_e32 v62, 1.0, v62
	v_rcp_f32_e32 v62, v62
	v_pk_fma_f32 v[58:59], v[84:85], v[58:59], v[64:65]
	v_mul_f32_e32 v50, v50, v62
	v_mul_f32_e32 v50, v50, v58
	v_mul_f32_e32 v58, 0xbfb8aa3b, v51
	v_exp_f32_e32 v58, v58
	v_pk_fma_f32 v[62:63], v[38:39], v[96:97], v[100:101]
	v_add_f32_e32 v58, 1.0, v58
	v_rcp_f32_e32 v58, v58
	v_pk_fma_f32 v[62:63], v[190:191], v[92:93], v[62:63]
	v_mul_f32_e32 v51, v51, v58
	v_mul_f32_e32 v58, 0xbfb8aa3b, v52
	v_exp_f32_e32 v58, v58
	v_mul_f32_e32 v51, v51, v59
	v_pk_fma_f32 v[62:63], v[198:199], v[84:85], v[62:63]
	v_add_f32_e32 v58, 1.0, v58
	v_rcp_f32_e32 v58, v58
	s_nop 0
	v_mul_f32_e32 v52, v52, v58
	v_mul_f32_e32 v58, v52, v60
	v_mul_f32_e32 v52, 0xbfb8aa3b, v53
	v_exp_f32_e32 v52, v52
	s_nop 0
	v_add_f32_e32 v52, 1.0, v52
	v_rcp_f32_e32 v52, v52
	s_nop 0
	v_mul_f32_e32 v52, v53, v52
	v_mul_f32_e32 v53, v52, v61
	v_cvt_pk_bf16_f32 v53, v58, v53
	v_pk_fma_f32 v[58:59], v[34:35], v[80:81], v[88:89]
	v_pk_fma_f32 v[34:35], v[34:35], v[76:77], v[42:43]
	v_pk_fma_f32 v[42:43], v[48:49], v[98:99], v[102:103]
	v_pk_fma_f32 v[34:35], v[186:187], v[72:73], v[34:35]
	v_pk_fma_f32 v[60:61], v[40:41], v[98:99], v[102:103]
	v_pk_fma_f32 v[40:41], v[40:41], v[94:95], v[42:43]
	v_mul_f32_e32 v42, 0xbfb8aa3b, v34
	v_exp_f32_e32 v42, v42
	v_pk_fma_f32 v[58:59], v[186:187], v[76:77], v[58:59]
	v_cvt_pk_bf16_f32 v52, v50, v51
	v_pk_fma_f32 v[50:51], v[36:37], v[82:83], v[90:91]
	v_add_f32_e32 v42, 1.0, v42
	v_pk_fma_f32 v[58:59], v[194:195], v[72:73], v[58:59]
	v_rcp_f32_e32 v42, v42
	v_mul_f32_e32 v64, 0xbfb8aa3b, v58
	v_exp_f32_e32 v64, v64
	v_pk_fma_f32 v[36:37], v[36:37], v[78:79], v[44:45]
	v_pk_fma_f32 v[44:45], v[46:47], v[96:97], v[100:101]
	v_mul_f32_e32 v34, v34, v42
	v_pk_fma_f32 v[38:39], v[38:39], v[92:93], v[44:45]
	v_add_f32_e32 v64, 1.0, v64
	v_pk_fma_f32 v[38:39], v[190:191], v[84:85], v[38:39]
	v_rcp_f32_e32 v64, v64
	v_mul_f32_e32 v34, v38, v34
	v_mul_f32_e32 v38, 0xbfb8aa3b, v35
	v_exp_f32_e32 v38, v38
	v_mul_f32_e32 v58, v58, v64
	v_mul_f32_e32 v58, v62, v58
	v_mul_f32_e32 v62, 0xbfb8aa3b, v59
	v_add_f32_e32 v38, 1.0, v38
	v_rcp_f32_e32 v38, v38
	v_exp_f32_e32 v62, v62
	v_pk_fma_f32 v[36:37], v[188:189], v[74:75], v[36:37]
	v_pk_fma_f32 v[50:51], v[188:189], v[78:79], v[50:51]
	v_mul_f32_e32 v35, v35, v38
	v_mul_f32_e32 v38, 0xbfb8aa3b, v36
	v_exp_f32_e32 v38, v38
	v_add_f32_e32 v62, 1.0, v62
	v_rcp_f32_e32 v62, v62
	v_pk_fma_f32 v[50:51], v[196:197], v[74:75], v[50:51]
	v_add_f32_e32 v38, 1.0, v38
	v_rcp_f32_e32 v38, v38
	v_mul_f32_e32 v59, v59, v62
	v_mul_f32_e32 v62, 0xbfb8aa3b, v50
	v_exp_f32_e32 v62, v62
	v_mul_f32_e32 v36, v36, v38
	v_mul_f32_e32 v38, 0xbfb8aa3b, v37
	v_exp_f32_e32 v38, v38
	v_add_f32_e32 v62, 1.0, v62
	v_rcp_f32_e32 v62, v62
	v_pk_fma_f32 v[60:61], v[192:193], v[94:95], v[60:61]
	v_add_f32_e32 v38, 1.0, v38
	v_rcp_f32_e32 v38, v38
	v_pk_fma_f32 v[60:61], v[200:201], v[86:87], v[60:61]
	v_mul_f32_e32 v50, v50, v62
	v_mul_f32_e32 v60, v60, v50
	v_mul_f32_e32 v50, 0xbfb8aa3b, v51
	v_exp_f32_e32 v50, v50
	v_pk_fma_f32 v[40:41], v[192:193], v[86:87], v[40:41]
	v_mul_f32_e32 v35, v39, v35
	v_mul_f32_e32 v36, v40, v36
	v_mul_f32_e32 v37, v37, v38
	v_mul_f32_e32 v37, v41, v37
	v_cvt_pk_bf16_f32 v34, v34, v35
	v_cvt_pk_bf16_f32 v35, v36, v37


	v_add_f32_e32 v50, 1.0, v50

	v_rcp_f32_e32 v50, v50


	ds_read_b128 v[44:47], v248 offset:1040


	ds_read_b128 v[36:39], v248 offset:16
	v_mul_f32_e32 v59, v63, v59
	ds_read_b128 v[78:81], v248 offset:3088


	v_mul_f32_e32 v50, v51, v50

	v_mul_f32_e32 v51, v61, v50
	v_cvt_pk_bf16_f32 v50, v58, v59

	v_cvt_pk_bf16_f32 v51, v60, v51
	ds_read_b128 v[60:63], v248 offset:2064
	ds_read_b128 v[74:77], v248 offset:1552


	ds_read_b128 v[40:43], v248 offset:528
	v_mov_b32_e32 v98, 0
	ds_read_b128 v[82:85], v248 offset:2576
	ds_read_b128 v[86:89], v248 offset:3600
	v_mov_b32_e32 v102, 0
	v_mov_b32_e32 v103, 0
	v_mov_b32_e32 v90, 0
	v_mov_b32_e32 v91, 0
	v_mov_b32_e32 v92, 0
	v_mov_b32_e32 v93, 0
	s_cbranch_vccnz .LBB0_1237
	ds_read_b128 v[90:93], v221 offset:16
	ds_read_b128 v[102:105], v222 offset:16
